# compress tail: 144 redundant spill v_readlane reloads removed (same lane already in the same SGPR, straight-line region)
# speedup vs baseline: 1.0034x; 1.0034x over previous
; DEV float lo_f(unsigned w) { return __uint_as_float(w << 16); }
; DEV float hi_f(unsigned w) { return __uint_as_float(w & 0xFFFF0000u); }
; DEV f32x4 mfma16(bf16x8 a, bf16x8 b, f32x4 c) { return __builtin_amdgcn_mfma_f32_16x16x32_bf16(a, b, c, 0, 0, 0); }
; __device__ void compress_block_item(const Params& P, int l, int bitem, char* smem) {
;     ...
; #pragma unroll 4
;   for (int k2 = 0; k2 < 16; ++k2) {
;     const int ks = w * 16 + k2;
;     const int tl = ks >> 1, d0 = (ks & 1) * 32 + kq * 8;
;     const uint4 raw = *(const uint4*)(src + (size_t)tl * HS + d0);
;     const float4 p0 = *(const float4*)(pos + tl * 64 + d0), p1 = *(const float4*)(pos + tl * 64 + d0 + 4);
;     float v[8];
;     v[0] = lo_f(raw.x) + p0.x; v[1] = hi_f(raw.x) + p0.y; v[2] = lo_f(raw.y) + p0.z; v[3] = hi_f(raw.y) + p0.w;
;     v[4] = lo_f(raw.z) + p1.x; v[5] = hi_f(raw.z) + p1.y; v[6] = lo_f(raw.w) + p1.z; v[7] = hi_f(raw.w) + p1.w;
;     const bf16x8 af = pack8(v);
; #pragma unroll
;     for (int nt = 0; nt < 4; ++nt) {
;       const bf16x8 bfr = *(const bf16x8*)(W1T + (size_t)(nt * 16 + r16) * 2048 + ks * 32 + kq * 8);
;       acc[nt] = mfma16(af, bfr, acc[nt]);
;     }
;   }
.LBB0_301:
	v_ashrrev_i32_e32 v240, 1, v37
	v_mov_b32_e32 v241, v177
	v_mad_i64_i32 v[236:237], s[44:45], v240, s46, v[16:17]
	v_lshlrev_b32_e32 v242, 8, v240
	v_mov_b32_e32 v243, v177
	v_lshl_add_u64 v[238:239], v[242:243], 0, v[18:19]
	v_add_co_u32_e32 v28, vcc, s2, v20
	s_nop 1
	v_addc_co_u32_e32 v29, vcc, 0, v21, vcc
	v_add_co_u32_e32 v26, vcc, s42, v20
	s_nop 1
	v_addc_co_u32_e32 v27, vcc, 0, v21, vcc
	v_add_co_u32_e32 v24, vcc, s43, v20
	s_nop 1
	v_addc_co_u32_e32 v25, vcc, 0, v21, vcc
	s_mov_b64 s[40:41], 0x1030
	global_load_dwordx4 v[88:91], v[236:237], off
	global_load_dwordx4 v[92:95], v[238:239], off
	global_load_dwordx4 v[96:99], v[238:239], off offset:16
	global_load_dwordx4 v[100:103], v[236:237], off offset:64
	global_load_dwordx4 v[104:107], v[238:239], off offset:128
	global_load_dwordx4 v[108:111], v[238:239], off offset:144
	global_load_dwordx4 v[112:115], v[20:21], off
	global_load_dwordx4 v[116:119], v[28:29], off
	global_load_dwordx4 v[120:123], v[26:27], off
	global_load_dwordx4 v[124:127], v[24:25], off
	global_load_dwordx4 v[128:131], v[20:21], off offset:64
	global_load_dwordx4 v[132:135], v[28:29], off offset:64
	global_load_dwordx4 v[136:139], v[26:27], off offset:64
	global_load_dwordx4 v[140:143], v[24:25], off offset:64
	v_lshl_add_u64 v[236:237], v[236:237], 0, s[40:41]
	global_load_dwordx4 v[144:147], v[236:237], off
	global_load_dwordx4 v[148:151], v[238:239], off offset:256
	global_load_dwordx4 v[152:155], v[238:239], off offset:272
	global_load_dwordx4 v[156:159], v[236:237], off offset:64
	global_load_dwordx4 v[160:163], v[238:239], off offset:384
	global_load_dwordx4 v[164:167], v[238:239], off offset:400
	global_load_dwordx4 v[168:171], v[20:21], off offset:128
	global_load_dwordx4 v[172:175], v[28:29], off offset:128
	global_load_dwordx4 v[180:183], v[26:27], off offset:128
	global_load_dwordx4 v[184:187], v[24:25], off offset:128
	global_load_dwordx4 v[188:191], v[20:21], off offset:192
	global_load_dwordx4 v[192:195], v[28:29], off offset:192
	global_load_dwordx4 v[196:199], v[26:27], off offset:192
	global_load_dwordx4 v[228:231], v[24:25], off offset:192
	v_lshl_add_u64 v[236:237], v[236:237], 0, s[40:41]
	s_waitcnt vmcnt(14)
	v_lshlrev_b32_e32 v42, 16, v88
	v_and_b32_e32 v43, 0xffff0000, v88
	v_lshlrev_b32_e32 v44, 16, v89
	v_and_b32_e32 v45, 0xffff0000, v89
	v_lshlrev_b32_e32 v46, 16, v90
	v_and_b32_e32 v47, 0xffff0000, v90
	v_lshlrev_b32_e32 v48, 16, v91
	v_and_b32_e32 v49, 0xffff0000, v91
	v_pk_add_f32 v[42:43], v[92:93], v[42:43]
	v_pk_add_f32 v[44:45], v[94:95], v[44:45]
	v_pk_add_f32 v[46:47], v[96:97], v[46:47]
	v_pk_add_f32 v[48:49], v[98:99], v[48:49]
	v_cvt_pk_bf16_f32 v38, v42, v43
	v_cvt_pk_bf16_f32 v39, v44, v45
	v_cvt_pk_bf16_f32 v40, v46, v47
	v_cvt_pk_bf16_f32 v41, v48, v49
	s_nop 1
	v_mfma_f32_16x16x32_bf16 v[0:3], v[38:41], v[112:115], v[0:3]
	v_mfma_f32_16x16x32_bf16 v[4:7], v[38:41], v[116:119], v[4:7]
	v_mfma_f32_16x16x32_bf16 v[8:11], v[38:41], v[120:123], v[8:11]
	v_mfma_f32_16x16x32_bf16 v[12:15], v[38:41], v[124:127], v[12:15]
	v_lshlrev_b32_e32 v42, 16, v100
	v_and_b32_e32 v43, 0xffff0000, v100
	v_lshlrev_b32_e32 v44, 16, v101
	v_and_b32_e32 v45, 0xffff0000, v101
	v_lshlrev_b32_e32 v46, 16, v102
	v_and_b32_e32 v47, 0xffff0000, v102
	v_lshlrev_b32_e32 v48, 16, v103
	v_and_b32_e32 v49, 0xffff0000, v103
	v_pk_add_f32 v[42:43], v[104:105], v[42:43]
	v_pk_add_f32 v[44:45], v[106:107], v[44:45]
	v_pk_add_f32 v[46:47], v[108:109], v[46:47]
	v_pk_add_f32 v[48:49], v[110:111], v[48:49]
	v_cvt_pk_bf16_f32 v232, v42, v43
	v_cvt_pk_bf16_f32 v233, v44, v45
	v_cvt_pk_bf16_f32 v234, v46, v47
	v_cvt_pk_bf16_f32 v235, v48, v49
	s_nop 1
	v_mfma_f32_16x16x32_bf16 v[0:3], v[232:235], v[128:131], v[0:3]
	v_mfma_f32_16x16x32_bf16 v[4:7], v[232:235], v[132:135], v[4:7]
	v_mfma_f32_16x16x32_bf16 v[8:11], v[232:235], v[136:139], v[8:11]
	v_mfma_f32_16x16x32_bf16 v[12:15], v[232:235], v[140:143], v[12:15]
	global_load_dwordx4 v[88:91], v[236:237], off
	global_load_dwordx4 v[92:95], v[238:239], off offset:512
	global_load_dwordx4 v[96:99], v[238:239], off offset:528
	global_load_dwordx4 v[100:103], v[236:237], off offset:64
	global_load_dwordx4 v[104:107], v[238:239], off offset:640
	global_load_dwordx4 v[108:111], v[238:239], off offset:656
	global_load_dwordx4 v[112:115], v[20:21], off offset:256
	global_load_dwordx4 v[116:119], v[28:29], off offset:256
	global_load_dwordx4 v[120:123], v[26:27], off offset:256
	global_load_dwordx4 v[124:127], v[24:25], off offset:256
	global_load_dwordx4 v[128:131], v[20:21], off offset:320
	global_load_dwordx4 v[132:135], v[28:29], off offset:320
	global_load_dwordx4 v[136:139], v[26:27], off offset:320
	global_load_dwordx4 v[140:143], v[24:25], off offset:320
	v_lshl_add_u64 v[236:237], v[236:237], 0, s[40:41]
	s_waitcnt vmcnt(14)
; DEV float lo_f(unsigned w) { return __uint_as_float(w << 16); }
; DEV float hi_f(unsigned w) { return __uint_as_float(w & 0xFFFF0000u); }
; DEV f32x4 mfma16(bf16x8 a, bf16x8 b, f32x4 c) { return __builtin_amdgcn_mfma_f32_16x16x32_bf16(a, b, c, 0, 0, 0); }
; __device__ void compress_block_item(const Params& P, int l, int bitem, char* smem) {
;     ...
; #pragma unroll 4
;   for (int k2 = 0; k2 < 16; ++k2) {
;     const int ks = w * 16 + k2;
;     const int tl = ks >> 1, d0 = (ks & 1) * 32 + kq * 8;
;     const uint4 raw = *(const uint4*)(src + (size_t)tl * HS + d0);
;     const float4 p0 = *(const float4*)(pos + tl * 64 + d0), p1 = *(const float4*)(pos + tl * 64 + d0 + 4);
;     float v[8];
;     v[0] = lo_f(raw.x) + p0.x; v[1] = hi_f(raw.x) + p0.y; v[2] = lo_f(raw.y) + p0.z; v[3] = hi_f(raw.y) + p0.w;
;     v[4] = lo_f(raw.z) + p1.x; v[5] = hi_f(raw.z) + p1.y; v[6] = lo_f(raw.w) + p1.z; v[7] = hi_f(raw.w) + p1.w;
;     const bf16x8 af = pack8(v);
; #pragma unroll
;     for (int nt = 0; nt < 4; ++nt) {
;       const bf16x8 bfr = *(const bf16x8*)(W1T + (size_t)(nt * 16 + r16) * 2048 + ks * 32 + kq * 8);
;       acc[nt] = mfma16(af, bfr, acc[nt]);
;     }
;   }
	v_lshlrev_b32_e32 v42, 16, v144
	v_and_b32_e32 v43, 0xffff0000, v144
	v_lshlrev_b32_e32 v44, 16, v145
	v_and_b32_e32 v45, 0xffff0000, v145
	v_lshlrev_b32_e32 v46, 16, v146
	v_and_b32_e32 v47, 0xffff0000, v146
	v_lshlrev_b32_e32 v48, 16, v147
	v_and_b32_e32 v49, 0xffff0000, v147
	v_pk_add_f32 v[42:43], v[148:149], v[42:43]
	v_pk_add_f32 v[44:45], v[150:151], v[44:45]
	v_pk_add_f32 v[46:47], v[152:153], v[46:47]
	v_pk_add_f32 v[48:49], v[154:155], v[48:49]
	v_cvt_pk_bf16_f32 v38, v42, v43
	v_cvt_pk_bf16_f32 v39, v44, v45
	v_cvt_pk_bf16_f32 v40, v46, v47
	v_cvt_pk_bf16_f32 v41, v48, v49
	s_nop 1
	v_mfma_f32_16x16x32_bf16 v[0:3], v[38:41], v[168:171], v[0:3]
	v_mfma_f32_16x16x32_bf16 v[4:7], v[38:41], v[172:175], v[4:7]
	v_mfma_f32_16x16x32_bf16 v[8:11], v[38:41], v[180:183], v[8:11]
	v_mfma_f32_16x16x32_bf16 v[12:15], v[38:41], v[184:187], v[12:15]
	v_lshlrev_b32_e32 v42, 16, v156
	v_and_b32_e32 v43, 0xffff0000, v156
	v_lshlrev_b32_e32 v44, 16, v157
	v_and_b32_e32 v45, 0xffff0000, v157
	v_lshlrev_b32_e32 v46, 16, v158
	v_and_b32_e32 v47, 0xffff0000, v158
	v_lshlrev_b32_e32 v48, 16, v159
	v_and_b32_e32 v49, 0xffff0000, v159
	v_pk_add_f32 v[42:43], v[160:161], v[42:43]
	v_pk_add_f32 v[44:45], v[162:163], v[44:45]
	v_pk_add_f32 v[46:47], v[164:165], v[46:47]
	v_pk_add_f32 v[48:49], v[166:167], v[48:49]
	v_cvt_pk_bf16_f32 v232, v42, v43
	v_cvt_pk_bf16_f32 v233, v44, v45
	v_cvt_pk_bf16_f32 v234, v46, v47
	v_cvt_pk_bf16_f32 v235, v48, v49
	s_nop 1
	v_mfma_f32_16x16x32_bf16 v[0:3], v[232:235], v[188:191], v[0:3]
	v_mfma_f32_16x16x32_bf16 v[4:7], v[232:235], v[192:195], v[4:7]
	v_mfma_f32_16x16x32_bf16 v[8:11], v[232:235], v[196:199], v[8:11]
	v_mfma_f32_16x16x32_bf16 v[12:15], v[232:235], v[228:231], v[12:15]
	global_load_dwordx4 v[144:147], v[236:237], off
	global_load_dwordx4 v[148:151], v[238:239], off offset:768
	global_load_dwordx4 v[152:155], v[238:239], off offset:784
	global_load_dwordx4 v[156:159], v[236:237], off offset:64
	global_load_dwordx4 v[160:163], v[238:239], off offset:896
	global_load_dwordx4 v[164:167], v[238:239], off offset:912
	global_load_dwordx4 v[168:171], v[20:21], off offset:384
	global_load_dwordx4 v[172:175], v[28:29], off offset:384
	global_load_dwordx4 v[180:183], v[26:27], off offset:384
	global_load_dwordx4 v[184:187], v[24:25], off offset:384
	global_load_dwordx4 v[188:191], v[20:21], off offset:448
	global_load_dwordx4 v[192:195], v[28:29], off offset:448
	global_load_dwordx4 v[196:199], v[26:27], off offset:448
	global_load_dwordx4 v[228:231], v[24:25], off offset:448
	v_lshl_add_u64 v[236:237], v[236:237], 0, s[40:41]
	s_waitcnt vmcnt(14)
	v_lshlrev_b32_e32 v42, 16, v88
	v_and_b32_e32 v43, 0xffff0000, v88
	v_lshlrev_b32_e32 v44, 16, v89
	v_and_b32_e32 v45, 0xffff0000, v89
	v_lshlrev_b32_e32 v46, 16, v90
	v_and_b32_e32 v47, 0xffff0000, v90
	v_lshlrev_b32_e32 v48, 16, v91
	v_and_b32_e32 v49, 0xffff0000, v91
	v_pk_add_f32 v[42:43], v[92:93], v[42:43]
	v_pk_add_f32 v[44:45], v[94:95], v[44:45]
	v_pk_add_f32 v[46:47], v[96:97], v[46:47]
	v_pk_add_f32 v[48:49], v[98:99], v[48:49]
	v_cvt_pk_bf16_f32 v38, v42, v43
	v_cvt_pk_bf16_f32 v39, v44, v45
	v_cvt_pk_bf16_f32 v40, v46, v47
	v_cvt_pk_bf16_f32 v41, v48, v49
	s_nop 1
	v_mfma_f32_16x16x32_bf16 v[0:3], v[38:41], v[112:115], v[0:3]
	v_mfma_f32_16x16x32_bf16 v[4:7], v[38:41], v[116:119], v[4:7]
	v_mfma_f32_16x16x32_bf16 v[8:11], v[38:41], v[120:123], v[8:11]
	v_mfma_f32_16x16x32_bf16 v[12:15], v[38:41], v[124:127], v[12:15]
	v_lshlrev_b32_e32 v42, 16, v100
	v_and_b32_e32 v43, 0xffff0000, v100
	v_lshlrev_b32_e32 v44, 16, v101
	v_and_b32_e32 v45, 0xffff0000, v101
	v_lshlrev_b32_e32 v46, 16, v102
	v_and_b32_e32 v47, 0xffff0000, v102
	v_lshlrev_b32_e32 v48, 16, v103
	v_and_b32_e32 v49, 0xffff0000, v103
	v_pk_add_f32 v[42:43], v[104:105], v[42:43]
	v_pk_add_f32 v[44:45], v[106:107], v[44:45]
	v_pk_add_f32 v[46:47], v[108:109], v[46:47]
	v_pk_add_f32 v[48:49], v[110:111], v[48:49]
	v_cvt_pk_bf16_f32 v232, v42, v43
	v_cvt_pk_bf16_f32 v233, v44, v45
	v_cvt_pk_bf16_f32 v234, v46, v47
	v_cvt_pk_bf16_f32 v235, v48, v49
	s_nop 1
	v_mfma_f32_16x16x32_bf16 v[0:3], v[232:235], v[128:131], v[0:3]
	v_mfma_f32_16x16x32_bf16 v[4:7], v[232:235], v[132:135], v[4:7]
	v_mfma_f32_16x16x32_bf16 v[8:11], v[232:235], v[136:139], v[8:11]
	v_mfma_f32_16x16x32_bf16 v[12:15], v[232:235], v[140:143], v[12:15]
	global_load_dwordx4 v[88:91], v[236:237], off
	global_load_dwordx4 v[92:95], v[238:239], off offset:1024
	global_load_dwordx4 v[96:99], v[238:239], off offset:1040
	global_load_dwordx4 v[100:103], v[236:237], off offset:64
	global_load_dwordx4 v[104:107], v[238:239], off offset:1152
	global_load_dwordx4 v[108:111], v[238:239], off offset:1168
	global_load_dwordx4 v[112:115], v[20:21], off offset:512
	global_load_dwordx4 v[116:119], v[28:29], off offset:512
	global_load_dwordx4 v[120:123], v[26:27], off offset:512
	global_load_dwordx4 v[124:127], v[24:25], off offset:512
	global_load_dwordx4 v[128:131], v[20:21], off offset:576
	global_load_dwordx4 v[132:135], v[28:29], off offset:576
	global_load_dwordx4 v[136:139], v[26:27], off offset:576
	global_load_dwordx4 v[140:143], v[24:25], off offset:576
	v_lshl_add_u64 v[236:237], v[236:237], 0, s[40:41]
	s_waitcnt vmcnt(14)
; DEV float lo_f(unsigned w) { return __uint_as_float(w << 16); }
; DEV float hi_f(unsigned w) { return __uint_as_float(w & 0xFFFF0000u); }
; DEV f32x4 mfma16(bf16x8 a, bf16x8 b, f32x4 c) { return __builtin_amdgcn_mfma_f32_16x16x32_bf16(a, b, c, 0, 0, 0); }
; __device__ void compress_block_item(const Params& P, int l, int bitem, char* smem) {
;     ...
; #pragma unroll 4
;   for (int k2 = 0; k2 < 16; ++k2) {
;     const int ks = w * 16 + k2;
;     const int tl = ks >> 1, d0 = (ks & 1) * 32 + kq * 8;
;     const uint4 raw = *(const uint4*)(src + (size_t)tl * HS + d0);
;     const float4 p0 = *(const float4*)(pos + tl * 64 + d0), p1 = *(const float4*)(pos + tl * 64 + d0 + 4);
;     float v[8];
;     v[0] = lo_f(raw.x) + p0.x; v[1] = hi_f(raw.x) + p0.y; v[2] = lo_f(raw.y) + p0.z; v[3] = hi_f(raw.y) + p0.w;
;     v[4] = lo_f(raw.z) + p1.x; v[5] = hi_f(raw.z) + p1.y; v[6] = lo_f(raw.w) + p1.z; v[7] = hi_f(raw.w) + p1.w;
;     const bf16x8 af = pack8(v);
; #pragma unroll
;     for (int nt = 0; nt < 4; ++nt) {
;       const bf16x8 bfr = *(const bf16x8*)(W1T + (size_t)(nt * 16 + r16) * 2048 + ks * 32 + kq * 8);
;       acc[nt] = mfma16(af, bfr, acc[nt]);
;     }
;   }
	v_lshlrev_b32_e32 v42, 16, v144
	v_and_b32_e32 v43, 0xffff0000, v144
	v_lshlrev_b32_e32 v44, 16, v145
	v_and_b32_e32 v45, 0xffff0000, v145
	v_lshlrev_b32_e32 v46, 16, v146
	v_and_b32_e32 v47, 0xffff0000, v146
	v_lshlrev_b32_e32 v48, 16, v147
	v_and_b32_e32 v49, 0xffff0000, v147
	v_pk_add_f32 v[42:43], v[148:149], v[42:43]
	v_pk_add_f32 v[44:45], v[150:151], v[44:45]
	v_pk_add_f32 v[46:47], v[152:153], v[46:47]
	v_pk_add_f32 v[48:49], v[154:155], v[48:49]
	v_cvt_pk_bf16_f32 v38, v42, v43
	v_cvt_pk_bf16_f32 v39, v44, v45
	v_cvt_pk_bf16_f32 v40, v46, v47
	v_cvt_pk_bf16_f32 v41, v48, v49
	s_nop 1
	v_mfma_f32_16x16x32_bf16 v[0:3], v[38:41], v[168:171], v[0:3]
	v_mfma_f32_16x16x32_bf16 v[4:7], v[38:41], v[172:175], v[4:7]
	v_mfma_f32_16x16x32_bf16 v[8:11], v[38:41], v[180:183], v[8:11]
	v_mfma_f32_16x16x32_bf16 v[12:15], v[38:41], v[184:187], v[12:15]
	v_lshlrev_b32_e32 v42, 16, v156
	v_and_b32_e32 v43, 0xffff0000, v156
	v_lshlrev_b32_e32 v44, 16, v157
	v_and_b32_e32 v45, 0xffff0000, v157
	v_lshlrev_b32_e32 v46, 16, v158
	v_and_b32_e32 v47, 0xffff0000, v158
	v_lshlrev_b32_e32 v48, 16, v159
	v_and_b32_e32 v49, 0xffff0000, v159
	v_pk_add_f32 v[42:43], v[160:161], v[42:43]
	v_pk_add_f32 v[44:45], v[162:163], v[44:45]
	v_pk_add_f32 v[46:47], v[164:165], v[46:47]
	v_pk_add_f32 v[48:49], v[166:167], v[48:49]
	v_cvt_pk_bf16_f32 v232, v42, v43
	v_cvt_pk_bf16_f32 v233, v44, v45
	v_cvt_pk_bf16_f32 v234, v46, v47
	v_cvt_pk_bf16_f32 v235, v48, v49
	s_nop 1
	v_mfma_f32_16x16x32_bf16 v[0:3], v[232:235], v[188:191], v[0:3]
	v_mfma_f32_16x16x32_bf16 v[4:7], v[232:235], v[192:195], v[4:7]
	v_mfma_f32_16x16x32_bf16 v[8:11], v[232:235], v[196:199], v[8:11]
	v_mfma_f32_16x16x32_bf16 v[12:15], v[232:235], v[228:231], v[12:15]
	global_load_dwordx4 v[144:147], v[236:237], off
	global_load_dwordx4 v[148:151], v[238:239], off offset:1280
	global_load_dwordx4 v[152:155], v[238:239], off offset:1296
	global_load_dwordx4 v[156:159], v[236:237], off offset:64
	global_load_dwordx4 v[160:163], v[238:239], off offset:1408
	global_load_dwordx4 v[164:167], v[238:239], off offset:1424
	global_load_dwordx4 v[168:171], v[20:21], off offset:640
	global_load_dwordx4 v[172:175], v[28:29], off offset:640
	global_load_dwordx4 v[180:183], v[26:27], off offset:640
	global_load_dwordx4 v[184:187], v[24:25], off offset:640
	global_load_dwordx4 v[188:191], v[20:21], off offset:704
	global_load_dwordx4 v[192:195], v[28:29], off offset:704
	global_load_dwordx4 v[196:199], v[26:27], off offset:704
	global_load_dwordx4 v[228:231], v[24:25], off offset:704
	v_lshl_add_u64 v[236:237], v[236:237], 0, s[40:41]
	s_waitcnt vmcnt(14)
	v_lshlrev_b32_e32 v42, 16, v88
	v_and_b32_e32 v43, 0xffff0000, v88
	v_lshlrev_b32_e32 v44, 16, v89
	v_and_b32_e32 v45, 0xffff0000, v89
	v_lshlrev_b32_e32 v46, 16, v90
	v_and_b32_e32 v47, 0xffff0000, v90
	v_lshlrev_b32_e32 v48, 16, v91
	v_and_b32_e32 v49, 0xffff0000, v91
	v_pk_add_f32 v[42:43], v[92:93], v[42:43]
	v_pk_add_f32 v[44:45], v[94:95], v[44:45]
	v_pk_add_f32 v[46:47], v[96:97], v[46:47]
	v_pk_add_f32 v[48:49], v[98:99], v[48:49]
	v_cvt_pk_bf16_f32 v38, v42, v43
	v_cvt_pk_bf16_f32 v39, v44, v45
	v_cvt_pk_bf16_f32 v40, v46, v47
	v_cvt_pk_bf16_f32 v41, v48, v49
	s_nop 1
	v_mfma_f32_16x16x32_bf16 v[0:3], v[38:41], v[112:115], v[0:3]
	v_mfma_f32_16x16x32_bf16 v[4:7], v[38:41], v[116:119], v[4:7]
	v_mfma_f32_16x16x32_bf16 v[8:11], v[38:41], v[120:123], v[8:11]
	v_mfma_f32_16x16x32_bf16 v[12:15], v[38:41], v[124:127], v[12:15]
	v_lshlrev_b32_e32 v42, 16, v100
	v_and_b32_e32 v43, 0xffff0000, v100
	v_lshlrev_b32_e32 v44, 16, v101
	v_and_b32_e32 v45, 0xffff0000, v101
	v_lshlrev_b32_e32 v46, 16, v102
	v_and_b32_e32 v47, 0xffff0000, v102
	v_lshlrev_b32_e32 v48, 16, v103
	v_and_b32_e32 v49, 0xffff0000, v103
	v_pk_add_f32 v[42:43], v[104:105], v[42:43]
	v_pk_add_f32 v[44:45], v[106:107], v[44:45]
	v_pk_add_f32 v[46:47], v[108:109], v[46:47]
	v_pk_add_f32 v[48:49], v[110:111], v[48:49]
	v_cvt_pk_bf16_f32 v232, v42, v43
	v_cvt_pk_bf16_f32 v233, v44, v45
	v_cvt_pk_bf16_f32 v234, v46, v47
	v_cvt_pk_bf16_f32 v235, v48, v49
	s_nop 1
	v_mfma_f32_16x16x32_bf16 v[0:3], v[232:235], v[128:131], v[0:3]
	v_mfma_f32_16x16x32_bf16 v[4:7], v[232:235], v[132:135], v[4:7]
	v_mfma_f32_16x16x32_bf16 v[8:11], v[232:235], v[136:139], v[8:11]
	v_mfma_f32_16x16x32_bf16 v[12:15], v[232:235], v[140:143], v[12:15]
	global_load_dwordx4 v[88:91], v[236:237], off
	global_load_dwordx4 v[92:95], v[238:239], off offset:1536
	global_load_dwordx4 v[96:99], v[238:239], off offset:1552
	global_load_dwordx4 v[100:103], v[236:237], off offset:64
	global_load_dwordx4 v[104:107], v[238:239], off offset:1664
	global_load_dwordx4 v[108:111], v[238:239], off offset:1680
	global_load_dwordx4 v[112:115], v[20:21], off offset:768
	global_load_dwordx4 v[116:119], v[28:29], off offset:768
	global_load_dwordx4 v[120:123], v[26:27], off offset:768
	global_load_dwordx4 v[124:127], v[24:25], off offset:768
	global_load_dwordx4 v[128:131], v[20:21], off offset:832
	global_load_dwordx4 v[132:135], v[28:29], off offset:832
	global_load_dwordx4 v[136:139], v[26:27], off offset:832
	global_load_dwordx4 v[140:143], v[24:25], off offset:832
	v_lshl_add_u64 v[236:237], v[236:237], 0, s[40:41]
	s_waitcnt vmcnt(14)
; DEV float lo_f(unsigned w) { return __uint_as_float(w << 16); }
; DEV float hi_f(unsigned w) { return __uint_as_float(w & 0xFFFF0000u); }
; DEV f32x4 mfma16(bf16x8 a, bf16x8 b, f32x4 c) { return __builtin_amdgcn_mfma_f32_16x16x32_bf16(a, b, c, 0, 0, 0); }
; __device__ void compress_block_item(const Params& P, int l, int bitem, char* smem) {
;     ...
; #pragma unroll 4
;   for (int k2 = 0; k2 < 16; ++k2) {
;     const int ks = w * 16 + k2;
;     const int tl = ks >> 1, d0 = (ks & 1) * 32 + kq * 8;
;     const uint4 raw = *(const uint4*)(src + (size_t)tl * HS + d0);
;     const float4 p0 = *(const float4*)(pos + tl * 64 + d0), p1 = *(const float4*)(pos + tl * 64 + d0 + 4);
;     float v[8];
;     v[0] = lo_f(raw.x) + p0.x; v[1] = hi_f(raw.x) + p0.y; v[2] = lo_f(raw.y) + p0.z; v[3] = hi_f(raw.y) + p0.w;
;     v[4] = lo_f(raw.z) + p1.x; v[5] = hi_f(raw.z) + p1.y; v[6] = lo_f(raw.w) + p1.z; v[7] = hi_f(raw.w) + p1.w;
;     const bf16x8 af = pack8(v);
; #pragma unroll
;     for (int nt = 0; nt < 4; ++nt) {
;       const bf16x8 bfr = *(const bf16x8*)(W1T + (size_t)(nt * 16 + r16) * 2048 + ks * 32 + kq * 8);
;       acc[nt] = mfma16(af, bfr, acc[nt]);
;     }
;   }
	v_lshlrev_b32_e32 v42, 16, v144
	v_and_b32_e32 v43, 0xffff0000, v144
	v_lshlrev_b32_e32 v44, 16, v145
	v_and_b32_e32 v45, 0xffff0000, v145
	v_lshlrev_b32_e32 v46, 16, v146
	v_and_b32_e32 v47, 0xffff0000, v146
	v_lshlrev_b32_e32 v48, 16, v147
	v_and_b32_e32 v49, 0xffff0000, v147
	v_pk_add_f32 v[42:43], v[148:149], v[42:43]
	v_pk_add_f32 v[44:45], v[150:151], v[44:45]
	v_pk_add_f32 v[46:47], v[152:153], v[46:47]
	v_pk_add_f32 v[48:49], v[154:155], v[48:49]
	v_cvt_pk_bf16_f32 v38, v42, v43
	v_cvt_pk_bf16_f32 v39, v44, v45
	v_cvt_pk_bf16_f32 v40, v46, v47
	v_cvt_pk_bf16_f32 v41, v48, v49
	s_nop 1
	v_mfma_f32_16x16x32_bf16 v[0:3], v[38:41], v[168:171], v[0:3]
	v_mfma_f32_16x16x32_bf16 v[4:7], v[38:41], v[172:175], v[4:7]
	v_mfma_f32_16x16x32_bf16 v[8:11], v[38:41], v[180:183], v[8:11]
	v_mfma_f32_16x16x32_bf16 v[12:15], v[38:41], v[184:187], v[12:15]
	v_lshlrev_b32_e32 v42, 16, v156
	v_and_b32_e32 v43, 0xffff0000, v156
	v_lshlrev_b32_e32 v44, 16, v157
	v_and_b32_e32 v45, 0xffff0000, v157
	v_lshlrev_b32_e32 v46, 16, v158
	v_and_b32_e32 v47, 0xffff0000, v158
	v_lshlrev_b32_e32 v48, 16, v159
	v_and_b32_e32 v49, 0xffff0000, v159
	v_pk_add_f32 v[42:43], v[160:161], v[42:43]
	v_pk_add_f32 v[44:45], v[162:163], v[44:45]
	v_pk_add_f32 v[46:47], v[164:165], v[46:47]
	v_pk_add_f32 v[48:49], v[166:167], v[48:49]
	v_cvt_pk_bf16_f32 v232, v42, v43
	v_cvt_pk_bf16_f32 v233, v44, v45
	v_cvt_pk_bf16_f32 v234, v46, v47
	v_cvt_pk_bf16_f32 v235, v48, v49
	s_nop 1
	v_mfma_f32_16x16x32_bf16 v[0:3], v[232:235], v[188:191], v[0:3]
	v_mfma_f32_16x16x32_bf16 v[4:7], v[232:235], v[192:195], v[4:7]
	v_mfma_f32_16x16x32_bf16 v[8:11], v[232:235], v[196:199], v[8:11]
	v_mfma_f32_16x16x32_bf16 v[12:15], v[232:235], v[228:231], v[12:15]
	global_load_dwordx4 v[144:147], v[236:237], off
	global_load_dwordx4 v[148:151], v[238:239], off offset:1792
	global_load_dwordx4 v[152:155], v[238:239], off offset:1808
	global_load_dwordx4 v[156:159], v[236:237], off offset:64
	global_load_dwordx4 v[160:163], v[238:239], off offset:1920
	global_load_dwordx4 v[164:167], v[238:239], off offset:1936
	global_load_dwordx4 v[168:171], v[20:21], off offset:896
	global_load_dwordx4 v[172:175], v[28:29], off offset:896
	global_load_dwordx4 v[180:183], v[26:27], off offset:896
	global_load_dwordx4 v[184:187], v[24:25], off offset:896
	global_load_dwordx4 v[188:191], v[20:21], off offset:960
	global_load_dwordx4 v[192:195], v[28:29], off offset:960
	global_load_dwordx4 v[196:199], v[26:27], off offset:960
	global_load_dwordx4 v[228:231], v[24:25], off offset:960
	v_lshl_add_u64 v[236:237], v[236:237], 0, s[40:41]
	s_waitcnt vmcnt(14)
	v_lshlrev_b32_e32 v42, 16, v88
	v_and_b32_e32 v43, 0xffff0000, v88
	v_lshlrev_b32_e32 v44, 16, v89
	v_and_b32_e32 v45, 0xffff0000, v89
	v_lshlrev_b32_e32 v46, 16, v90
	v_and_b32_e32 v47, 0xffff0000, v90
	v_lshlrev_b32_e32 v48, 16, v91
	v_and_b32_e32 v49, 0xffff0000, v91
	v_pk_add_f32 v[42:43], v[92:93], v[42:43]
	v_pk_add_f32 v[44:45], v[94:95], v[44:45]
	v_pk_add_f32 v[46:47], v[96:97], v[46:47]
	v_pk_add_f32 v[48:49], v[98:99], v[48:49]
	v_cvt_pk_bf16_f32 v38, v42, v43
	v_cvt_pk_bf16_f32 v39, v44, v45
	v_cvt_pk_bf16_f32 v40, v46, v47
	v_cvt_pk_bf16_f32 v41, v48, v49
	s_nop 1
	v_mfma_f32_16x16x32_bf16 v[0:3], v[38:41], v[112:115], v[0:3]
	v_mfma_f32_16x16x32_bf16 v[4:7], v[38:41], v[116:119], v[4:7]
	v_mfma_f32_16x16x32_bf16 v[8:11], v[38:41], v[120:123], v[8:11]
	v_mfma_f32_16x16x32_bf16 v[12:15], v[38:41], v[124:127], v[12:15]
	v_lshlrev_b32_e32 v42, 16, v100
	v_and_b32_e32 v43, 0xffff0000, v100
	v_lshlrev_b32_e32 v44, 16, v101
	v_and_b32_e32 v45, 0xffff0000, v101
	v_lshlrev_b32_e32 v46, 16, v102
	v_and_b32_e32 v47, 0xffff0000, v102
	v_lshlrev_b32_e32 v48, 16, v103
	v_and_b32_e32 v49, 0xffff0000, v103
	v_pk_add_f32 v[42:43], v[104:105], v[42:43]
	v_pk_add_f32 v[44:45], v[106:107], v[44:45]
	v_pk_add_f32 v[46:47], v[108:109], v[46:47]
	v_pk_add_f32 v[48:49], v[110:111], v[48:49]
	v_cvt_pk_bf16_f32 v232, v42, v43
	v_cvt_pk_bf16_f32 v233, v44, v45
	v_cvt_pk_bf16_f32 v234, v46, v47
	v_cvt_pk_bf16_f32 v235, v48, v49
	s_nop 1
	v_mfma_f32_16x16x32_bf16 v[0:3], v[232:235], v[128:131], v[0:3]
	v_mfma_f32_16x16x32_bf16 v[4:7], v[232:235], v[132:135], v[4:7]
	v_mfma_f32_16x16x32_bf16 v[8:11], v[232:235], v[136:139], v[8:11]
	v_mfma_f32_16x16x32_bf16 v[12:15], v[232:235], v[140:143], v[12:15]
	s_waitcnt vmcnt(0)
; DEV float lo_f(unsigned w) { return __uint_as_float(w << 16); }
; DEV float hi_f(unsigned w) { return __uint_as_float(w & 0xFFFF0000u); }
; DEV f32x4 mfma16(bf16x8 a, bf16x8 b, f32x4 c) { return __builtin_amdgcn_mfma_f32_16x16x32_bf16(a, b, c, 0, 0, 0); }
; __device__ void compress_block_item(const Params& P, int l, int bitem, char* smem) {
;     ...
; #pragma unroll 4
;   for (int k2 = 0; k2 < 16; ++k2) {
;     const int ks = w * 16 + k2;
;     const int tl = ks >> 1, d0 = (ks & 1) * 32 + kq * 8;
;     const uint4 raw = *(const uint4*)(src + (size_t)tl * HS + d0);
;     const float4 p0 = *(const float4*)(pos + tl * 64 + d0), p1 = *(const float4*)(pos + tl * 64 + d0 + 4);
;     float v[8];
;     v[0] = lo_f(raw.x) + p0.x; v[1] = hi_f(raw.x) + p0.y; v[2] = lo_f(raw.y) + p0.z; v[3] = hi_f(raw.y) + p0.w;
;     v[4] = lo_f(raw.z) + p1.x; v[5] = hi_f(raw.z) + p1.y; v[6] = lo_f(raw.w) + p1.z; v[7] = hi_f(raw.w) + p1.w;
;     const bf16x8 af = pack8(v);
; #pragma unroll
;     for (int nt = 0; nt < 4; ++nt) {
;       const bf16x8 bfr = *(const bf16x8*)(W1T + (size_t)(nt * 16 + r16) * 2048 + ks * 32 + kq * 8);
;       acc[nt] = mfma16(af, bfr, acc[nt]);
;     }
;   }
;   const float* b1 = (kv ? P.cmpv_b1 : P.cmpk_b1) + l * 64;
;   const float* w2 = (kv ? P.cmpv_w2 : P.cmpk_w2) + l * 64 * 64;
;   const float* b2 = (kv ? P.cmpv_b2 : P.cmpk_b2) + l * 64;
;   __syncthreads();
; #pragma unroll
;   for (int nt = 0; nt < 4; ++nt)
; #pragma unroll
;     for (int r = 0; r < 4; ++r) part[w * 1024 + (kq * 4 + r) * 64 + nt * 16 + r16] = acc[nt][r];
;   __syncthreads();
; #pragma unroll
;   for (int k = 0; k < 4; ++k) {
;     const int idx = tid + 256 * k;
;     const float sum = part[idx] + part[1024 + idx] + part[2048 + idx] + part[3072 + idx];
;     hid[idx] = gelu_t(sum + b1[idx & 63]);
	v_lshlrev_b32_e32 v42, 16, v144
	v_and_b32_e32 v43, 0xffff0000, v144
	v_lshlrev_b32_e32 v44, 16, v145
	v_and_b32_e32 v45, 0xffff0000, v145
	v_lshlrev_b32_e32 v46, 16, v146
	v_and_b32_e32 v47, 0xffff0000, v146
	v_lshlrev_b32_e32 v48, 16, v147
	v_and_b32_e32 v49, 0xffff0000, v147
	v_pk_add_f32 v[42:43], v[148:149], v[42:43]
	v_pk_add_f32 v[44:45], v[150:151], v[44:45]
	v_pk_add_f32 v[46:47], v[152:153], v[46:47]
	v_pk_add_f32 v[48:49], v[154:155], v[48:49]
	v_cvt_pk_bf16_f32 v38, v42, v43
	v_cvt_pk_bf16_f32 v39, v44, v45
	v_cvt_pk_bf16_f32 v40, v46, v47
	v_cvt_pk_bf16_f32 v41, v48, v49
	s_nop 1
	v_mfma_f32_16x16x32_bf16 v[0:3], v[38:41], v[168:171], v[0:3]
	v_mfma_f32_16x16x32_bf16 v[4:7], v[38:41], v[172:175], v[4:7]
	v_mfma_f32_16x16x32_bf16 v[8:11], v[38:41], v[180:183], v[8:11]
	v_mfma_f32_16x16x32_bf16 v[12:15], v[38:41], v[184:187], v[12:15]
	v_lshlrev_b32_e32 v42, 16, v156
	v_and_b32_e32 v43, 0xffff0000, v156
	v_lshlrev_b32_e32 v44, 16, v157
	v_and_b32_e32 v45, 0xffff0000, v157
	v_lshlrev_b32_e32 v46, 16, v158
	v_and_b32_e32 v47, 0xffff0000, v158
	v_lshlrev_b32_e32 v48, 16, v159
	v_and_b32_e32 v49, 0xffff0000, v159
	v_pk_add_f32 v[42:43], v[160:161], v[42:43]
	v_pk_add_f32 v[44:45], v[162:163], v[44:45]
	v_pk_add_f32 v[46:47], v[164:165], v[46:47]
	v_pk_add_f32 v[48:49], v[166:167], v[48:49]
	v_cvt_pk_bf16_f32 v232, v42, v43
	v_cvt_pk_bf16_f32 v233, v44, v45
	v_cvt_pk_bf16_f32 v234, v46, v47
	v_cvt_pk_bf16_f32 v235, v48, v49
	s_nop 1
	v_mfma_f32_16x16x32_bf16 v[0:3], v[232:235], v[188:191], v[0:3]
	v_mfma_f32_16x16x32_bf16 v[4:7], v[232:235], v[192:195], v[4:7]
	v_mfma_f32_16x16x32_bf16 v[8:11], v[232:235], v[196:199], v[8:11]
	v_mfma_f32_16x16x32_bf16 v[12:15], v[232:235], v[228:231], v[12:15]
	s_and_b32 s96, s6, 0x7f0
	s_lshl_b32 s2, s56, 8
	v_readlane_b32 s40, v251, 26
	v_readlane_b32 s68, v252, 36
	s_and_b64 s[38:39], s[38:39], exec
	v_readlane_b32 s41, v251, 27
	v_readlane_b32 s42, v251, 28
	v_readlane_b32 s43, v251, 29
	v_readlane_b32 s44, v251, 30
	v_readlane_b32 s45, v251, 31
	v_readlane_b32 s46, v251, 32
	v_readlane_b32 s47, v251, 33
	v_readlane_b32 s48, v251, 34
	v_readlane_b32 s49, v251, 35
	v_readlane_b32 s50, v251, 36
	v_readlane_b32 s51, v251, 37
	v_readlane_b32 s52, v251, 38
	v_readlane_b32 s53, v251, 39
	v_readlane_b32 s54, v251, 40
	v_readlane_b32 s55, v251, 41
	v_readlane_b32 s69, v252, 37
	v_readlane_b32 s70, v252, 38
	v_readlane_b32 s71, v252, 39
	v_readlane_b32 s72, v252, 40
	v_readlane_b32 s73, v252, 41
	v_readlane_b32 s74, v252, 42
	v_readlane_b32 s75, v252, 43
	v_readlane_b32 s76, v252, 44
	v_readlane_b32 s77, v252, 45
	v_readlane_b32 s78, v252, 46
	v_readlane_b32 s79, v252, 47
	v_readlane_b32 s80, v252, 48
	v_readlane_b32 s81, v252, 49
	v_readlane_b32 s82, v252, 50
	v_readlane_b32 s83, v252, 51
	s_cselect_b32 s38, s49, s71
	s_cselect_b32 s39, s48, s70
	s_cselect_b32 s41, s51, s73
	v_readlane_b32 s44, v251, 26
	v_readlane_b32 s45, v251, 27
	v_readlane_b32 s46, v251, 28
	v_readlane_b32 s47, v251, 29
	v_readlane_b32 s48, v251, 30
	v_readlane_b32 s49, v251, 31
	v_readlane_b32 s50, v251, 32
	v_readlane_b32 s51, v251, 33
	v_readlane_b32 s52, v251, 34
	v_readlane_b32 s53, v251, 35
	v_readlane_b32 s54, v251, 36
	v_readlane_b32 s55, v251, 37
	v_readlane_b32 s56, v251, 38
	v_readlane_b32 s57, v251, 39
	v_readlane_b32 s58, v251, 40
	v_readlane_b32 s59, v251, 41
	s_cselect_b32 s42, s54, s72
	s_cselect_b32 s40, s57, s75
	v_lshlrev_b32_e32 v16, 12, v33
	v_lshlrev_b32_e32 v17, 10, v36
	v_lshlrev_b32_e32 v18, 2, v35
	v_readlane_b32 s46, v248, 23
	s_cselect_b32 s43, s56, s74
	v_or3_b32 v16, v16, v17, v18
	v_readlane_b32 s47, v248, 24
	s_add_u32 s44, s39, s46
	s_barrier
	ds_write2_b32 v16, v0, v4 offset1:16
	ds_write2_b32 v16, v1, v5 offset0:64 offset1:80
	ds_write2_b32 v16, v2, v6 offset0:128 offset1:144
	ds_write2_b32 v16, v3, v7 offset0:192 offset1:208
	ds_write2_b32 v16, v8, v12 offset0:32 offset1:48
	ds_write2_b32 v16, v9, v13 offset0:96 offset1:112
	ds_write2_b32 v16, v10, v14 offset0:160 offset1:176
	ds_write2_b32 v16, v11, v15 offset0:224 offset1:240
	s_addc_u32 s45, s38, s47
	v_lshlrev_b32_e32 v176, 2, v32
	v_lshlrev_b32_e32 v0, 2, v34
	s_waitcnt lgkmcnt(0)
	s_barrier
	ds_read2st64_b32 v[2:3], v0 offset1:4
	ds_read2st64_b32 v[4:5], v0 offset0:16 offset1:20
	global_load_dword v10, v176, s[44:45]
	ds_read2st64_b32 v[6:7], v0 offset0:32 offset1:36
	ds_read2st64_b32 v[8:9], v0 offset0:48 offset1:52
	v_readlane_b32 s38, v248, 25
	s_waitcnt lgkmcnt(2)
	v_add_f32_e32 v1, v2, v4
	v_readlane_b32 s39, v248, 26
	s_waitcnt lgkmcnt(1)
	v_add_f32_e32 v1, v1, v6
	s_waitcnt lgkmcnt(0)
	v_add_f32_e32 v1, v1, v8
	s_add_u32 s38, s42, s38
	s_addc_u32 s39, s41, s39
	v_readlane_b32 s68, v249, 21
	v_readlane_b32 s78, v249, 31
	v_readlane_b32 s79, v249, 32
	v_readlane_b32 s69, v249, 22
	v_readlane_b32 s70, v249, 23
	v_readlane_b32 s71, v249, 24
	v_readlane_b32 s72, v249, 25
	v_readlane_b32 s73, v249, 26
	v_readlane_b32 s74, v249, 27
	v_readlane_b32 s75, v249, 28
	v_readlane_b32 s76, v249, 29
	v_readlane_b32 s77, v249, 30
	v_readlane_b32 s80, v249, 33
	v_readlane_b32 s81, v249, 34
	v_readlane_b32 s82, v249, 35
	v_readlane_b32 s83, v249, 36
	s_waitcnt vmcnt(0)
; DEV float gelu_t(float x) {
;   float z = 0.7978845608028654f * (x + 0.044715f * x * x * x);
;   float e = __expf(2.f * z);
;   float th = 1.f - 2.f / (e + 1.f);
;   return 0.5f * x * (1.f + th);
; }
; __device__ void compress_block_item(const Params& P, int l, int bitem, char* smem) {
;     ...
; #pragma unroll
;   for (int k = 0; k < 4; ++k) {
;     const int idx = tid + 256 * k;
;     const float sum = part[idx] + part[1024 + idx] + part[2048 + idx] + part[3072 + idx];
;     hid[idx] = gelu_t(sum + b1[idx & 63]);
;   }
;   __syncthreads();
	v_add_f32_e32 v1, v1, v10
	v_mul_f32_e32 v2, 0x3d372713, v1
	v_mul_f32_e32 v2, v1, v2
	v_fma_f32 v2, v1, v2, v1
	v_mul_f32_e32 v2, 0x3f4c422a, v2
	v_add_f32_e32 v2, v2, v2
	v_mul_f32_e32 v2, 0x3fb8aa3b, v2
	v_exp_f32_e32 v2, v2
	v_mul_f32_e32 v1, 0.5, v1
	v_add_f32_e32 v2, 1.0, v2
	v_div_scale_f32 v4, s[44:45], v2, v2, 2.0
	v_rcp_f32_e32 v6, v4
	s_nop 0
	v_fma_f32 v8, -v4, v6, 1.0
	v_fmac_f32_e32 v6, v8, v6
	v_div_scale_f32 v8, vcc, 2.0, v2, 2.0
	v_mul_f32_e32 v11, v8, v6
	v_fma_f32 v12, -v4, v11, v8
	v_fmac_f32_e32 v11, v12, v6
	v_fma_f32 v4, -v4, v11, v8
	v_div_fmas_f32 v4, v4, v6, v11
	v_div_fixup_f32 v2, v4, v2, 2.0
	v_sub_f32_e32 v2, 1.0, v2
	v_add_f32_e32 v2, 1.0, v2
	v_mul_f32_e32 v1, v1, v2
	v_add_f32_e32 v2, v3, v5
	v_add_f32_e32 v2, v2, v7
	v_add_f32_e32 v2, v2, v9
	v_add_f32_e32 v2, v10, v2
	v_mul_f32_e32 v3, 0x3d372713, v2
	v_mul_f32_e32 v3, v2, v3
	v_fma_f32 v3, v2, v3, v2
	v_mul_f32_e32 v3, 0x3f4c422a, v3
	v_add_f32_e32 v3, v3, v3
	v_mul_f32_e32 v3, 0x3fb8aa3b, v3
	v_exp_f32_e32 v3, v3
	v_mul_f32_e32 v2, 0.5, v2
	v_add_f32_e32 v3, 1.0, v3
	v_div_scale_f32 v4, s[44:45], v3, v3, 2.0
	v_rcp_f32_e32 v5, v4
	s_nop 0
	v_fma_f32 v6, -v4, v5, 1.0
	v_fmac_f32_e32 v5, v6, v5
	v_div_scale_f32 v6, vcc, 2.0, v3, 2.0
	v_mul_f32_e32 v7, v6, v5
	v_fma_f32 v8, -v4, v7, v6
	v_fmac_f32_e32 v7, v8, v5
	v_fma_f32 v4, -v4, v7, v6
	v_div_fmas_f32 v4, v4, v5, v7
	v_div_fixup_f32 v3, v4, v3, 2.0
	v_sub_f32_e32 v3, 1.0, v3
	v_add_f32_e32 v3, 1.0, v3
	v_mul_f32_e32 v2, v2, v3
	ds_write2st64_b32 v0, v1, v2 offset0:64 offset1:68
	ds_read2st64_b32 v[2:3], v0 offset0:8 offset1:12
	ds_read2st64_b32 v[4:5], v0 offset0:24 offset1:28
	ds_read2st64_b32 v[6:7], v0 offset0:40 offset1:44
	ds_read2st64_b32 v[8:9], v0 offset0:56 offset1:60
	s_waitcnt lgkmcnt(2)
	v_add_f32_e32 v1, v2, v4
	s_waitcnt lgkmcnt(1)
	v_add_f32_e32 v1, v1, v6
	s_waitcnt lgkmcnt(0)
	v_add_f32_e32 v1, v1, v8
	v_add_f32_e32 v1, v10, v1
	v_mul_f32_e32 v2, 0x3d372713, v1
	v_mul_f32_e32 v2, v1, v2
	v_fma_f32 v2, v1, v2, v1
	v_mul_f32_e32 v2, 0x3f4c422a, v2
	v_add_f32_e32 v2, v2, v2
	v_mul_f32_e32 v2, 0x3fb8aa3b, v2
	v_exp_f32_e32 v2, v2
	v_mul_f32_e32 v1, 0.5, v1
	v_add_f32_e32 v2, 1.0, v2
	v_div_scale_f32 v4, s[44:45], v2, v2, 2.0
	v_rcp_f32_e32 v6, v4
	s_nop 0
	v_fma_f32 v8, -v4, v6, 1.0
	v_fmac_f32_e32 v6, v8, v6
	v_div_scale_f32 v8, vcc, 2.0, v2, 2.0
	v_mul_f32_e32 v11, v8, v6
	v_fma_f32 v12, -v4, v11, v8
	v_fmac_f32_e32 v11, v12, v6
	v_fma_f32 v4, -v4, v11, v8
	v_div_fmas_f32 v4, v4, v6, v11
	v_div_fixup_f32 v2, v4, v2, 2.0
	v_sub_f32_e32 v2, 1.0, v2
	v_add_f32_e32 v2, 1.0, v2
	v_mul_f32_e32 v1, v1, v2
	v_add_f32_e32 v2, v3, v5
	v_add_f32_e32 v2, v2, v7
	v_add_f32_e32 v2, v2, v9
	v_add_f32_e32 v2, v10, v2
	v_mul_f32_e32 v3, 0x3d372713, v2
	v_mul_f32_e32 v3, v2, v3
	v_fma_f32 v3, v2, v3, v2
	v_mul_f32_e32 v3, 0x3f4c422a, v3
	v_add_f32_e32 v3, v3, v3
	v_mul_f32_e32 v3, 0x3fb8aa3b, v3
	v_exp_f32_e32 v3, v3
	v_mul_f32_e32 v2, 0.5, v2
	v_add_f32_e32 v3, 1.0, v3
	v_div_scale_f32 v4, s[44:45], v3, v3, 2.0
	v_rcp_f32_e32 v5, v4
	s_mov_b32 s44, 0
	v_fma_f32 v6, -v4, v5, 1.0
	v_fmac_f32_e32 v5, v6, v5
	v_div_scale_f32 v6, vcc, 2.0, v3, 2.0
	v_mul_f32_e32 v7, v6, v5
	v_fma_f32 v8, -v4, v7, v6
	v_fmac_f32_e32 v7, v8, v5
	v_fma_f32 v4, -v4, v7, v6
	v_div_fmas_f32 v4, v4, v5, v7
	v_div_fixup_f32 v3, v4, v3, 2.0
	v_sub_f32_e32 v3, 1.0, v3
	v_add_f32_e32 v3, 1.0, v3
	v_mul_f32_e32 v2, v2, v3
	ds_write2st64_b32 v0, v1, v2 offset0:72 offset1:76
	s_waitcnt lgkmcnt(0)
	s_barrier
; __device__ void compress_block_item(const Params& P, int l, int bitem, char* smem) {
;     ...
;   float w2c[64];
; #pragma unroll
;   for (int k = 0; k < 64; ++k) w2c[k] = w2[k * 64 + lane];
;   const float bo = b2[lane];
; #pragma unroll 1
;   for (int r4 = 0; r4 < 4; ++r4) {
;     const int rr = w * 4 + r4;
;     float o = bo;
;     const float4* hp = (const float4*)(hid + rr * 64);
	v_lshl_add_u64 v[0:1], s[38:39], 0, v[176:177]
	global_load_dword v3, v176, s[38:39]
	global_load_dword v4, v176, s[38:39] offset:256
	global_load_dword v5, v176, s[38:39] offset:512
	global_load_dword v6, v176, s[38:39] offset:768
	global_load_dword v7, v176, s[38:39] offset:1024
	global_load_dword v8, v176, s[38:39] offset:1280
	global_load_dword v9, v176, s[38:39] offset:1536
	global_load_dword v10, v176, s[38:39] offset:1792
	global_load_dword v11, v176, s[38:39] offset:2048
	global_load_dword v12, v176, s[38:39] offset:2304
	global_load_dword v13, v176, s[38:39] offset:2560
	global_load_dword v14, v176, s[38:39] offset:2816
	global_load_dword v15, v176, s[38:39] offset:3072
	global_load_dword v16, v176, s[38:39] offset:3328
	global_load_dword v17, v176, s[38:39] offset:3584
	global_load_dword v18, v176, s[38:39] offset:3840
	s_movk_i32 s38, 0x1000
	v_add_co_u32_e32 v36, vcc, s38, v0
	s_movk_i32 s38, 0x3000
	s_nop 0
	v_addc_co_u32_e32 v37, vcc, 0, v1, vcc
	v_add_co_u32_e32 v52, vcc, s65, v0
	v_lshl_add_u32 v2, v33, 2, s96
	s_nop 0
	v_addc_co_u32_e32 v53, vcc, 0, v1, vcc
	global_load_dword v19, v[52:53], off offset:-4096
	global_load_dword v20, v[36:37], off offset:256
	global_load_dword v21, v[36:37], off offset:512
	global_load_dword v22, v[36:37], off offset:768
	global_load_dword v23, v[36:37], off offset:1024
	global_load_dword v24, v[36:37], off offset:1280
	global_load_dword v25, v[36:37], off offset:1536
	global_load_dword v26, v[36:37], off offset:1792
	global_load_dword v27, v[36:37], off offset:2048
	global_load_dword v28, v[36:37], off offset:2304
	global_load_dword v29, v[36:37], off offset:2560
	global_load_dword v30, v[36:37], off offset:2816
	global_load_dword v31, v[36:37], off offset:3072
	global_load_dword v34, v[36:37], off offset:3328
	global_load_dword v35, v[36:37], off offset:3584
	s_nop 0
	global_load_dword v36, v[36:37], off offset:3840
	s_nop 0
	global_load_dword v37, v[52:53], off
	global_load_dword v38, v[52:53], off offset:256
	global_load_dword v39, v[52:53], off offset:512
	global_load_dword v40, v[52:53], off offset:768
	global_load_dword v41, v[52:53], off offset:1024
	global_load_dword v42, v[52:53], off offset:1280
	global_load_dword v43, v[52:53], off offset:1536
	global_load_dword v44, v[52:53], off offset:1792
	global_load_dword v45, v[52:53], off offset:2048
	global_load_dword v46, v[52:53], off offset:2304
	global_load_dword v47, v[52:53], off offset:2560
	global_load_dword v48, v[52:53], off offset:2816
	global_load_dword v49, v[52:53], off offset:3072
	global_load_dword v50, v[52:53], off offset:3328
	global_load_dword v51, v[52:53], off offset:3584
	s_nop 0
	global_load_dword v52, v[52:53], off offset:3840
	v_add_co_u32_e32 v0, vcc, s38, v0
	s_add_u32 s38, s43, s46
	s_nop 0
	v_addc_co_u32_e32 v1, vcc, 0, v1, vcc
	global_load_dword v53, v[0:1], off
	global_load_dword v54, v[0:1], off offset:256
	global_load_dword v55, v[0:1], off offset:512
	global_load_dword v56, v[0:1], off offset:768
	global_load_dword v57, v[0:1], off offset:1024
	global_load_dword v58, v[0:1], off offset:1280
	global_load_dword v59, v[0:1], off offset:1536
	global_load_dword v60, v[0:1], off offset:1792
	global_load_dword v61, v[0:1], off offset:2048
	global_load_dword v62, v[0:1], off offset:2304
	global_load_dword v63, v[0:1], off offset:2560
	global_load_dword v64, v[0:1], off offset:2816
	global_load_dword v65, v[0:1], off offset:3072
	global_load_dword v66, v[0:1], off offset:3328
	global_load_dword v67, v[0:1], off offset:3584
	global_load_dword v68, v[0:1], off offset:3840
	s_addc_u32 s39, s40, s47
	global_load_dword v69, v176, s[38:39]
	v_lshlrev_b32_e32 v176, 1, v32
	v_lshl_add_u64 v[0:1], s[78:79], 0, v[176:177]
	v_or_b32_e32 v32, s64, v32
	v_lshl_add_u32 v33, v33, 10, v225
	s_waitcnt vmcnt(0)
	s_branch .LBB0_304
